# co-resident workgroup stagger: second workgroup of a CU (LDS base != 0) sleeps ~0.6us once at entry of GEMM phases 1,6,7,8 so the two workgroups alternate LDS-fill and MFMA segments
# speedup vs baseline: 1.0046x; 1.0042x over previous
; __global__ void __launch_bounds__(256, 2) hybrid_megakernel(Params p) {
;     ...
;   for (int ph = p.ph_lo; ph < p.ph_hi; ++ph) {
;     const int L = ph / NPH, s = ph % NPH;
;     if (s == 0 && L > 0) continue;
;     ...
;     if (s != ONLY) continue;
;     ...
;     switch (s) {
;       case 0: phase_convert(p, L, smem); break;
;       case 1: phase_in(p, L, smem); break;
;       case 2: phase_prep(p, L, smem); break;
;       case 3: phase_attn1(p, L, smem); break;
;       case 4: phase_attn2(p, smem); break;
;       case 5: phase_widen(p, smem); break;
;       case 6: phase_resid(p, p.u, 1024, p.wt_o, 1024, smem); break;
;       case 7: phase_up(p, smem); break;
;       case 8: phase_resid(p, p.ff, DFF, p.wt_down, DFF, smem); break;
;       case 9: phase_ple(p, L, smem); break;
;     }
.LBB0_4:
	v_writelane_b32 v255, s6, 31
	s_mov_b32 s98, 0x1c2
	s_lshr_b32 s98, s98, s6
	s_bitcmp1_b32 s98, 0
	s_cbranch_scc0 .Lstag_skip
	s_getreg_b32 s98, hwreg(HW_REG_LDS_ALLOC, 0, 12)
	s_cmp_eq_u32 s98, 0
	s_cbranch_scc1 .Lstag_skip
	s_sleep 24
.Lstag_skip:
	s_cmp_lt_i32 s6, 5
	s_cbranch_scc1 .LBB0_140
	v_readlane_b32 s2, v255, 31
	s_cmp_lt_i32 s2, 7
	s_mov_b64 s[2:3], -1
	s_cbranch_scc1 .LBB0_123
	v_readlane_b32 s2, v255, 31
	s_cmp_lt_i32 s2, 8
	s_mov_b64 s[2:3], -1
	s_cbranch_scc1 .LBB0_99
	v_readlane_b32 s2, v255, 31
	s_cmp_lt_i32 s2, 9
	s_mov_b64 s[2:3], -1
	s_cbranch_scc1 .LBB0_92
	v_readlane_b32 s2, v255, 31
	s_cmp_eq_u32 s2, 9
	s_cbranch_scc0 .LBB0_91
	v_readlane_b32 s2, v254, 36
	v_readlane_b32 s3, v254, 37
	v_readlane_b32 s16, v253, 48
	v_mov_b32_e32 v0, v224
	s_andn2_b64 vcc, exec, s[2:3]
	v_readlane_b32 s28, v253, 60
	v_readlane_b32 s29, v253, 61
	s_movk_i32 s6, 0x90
	s_mov_b32 s7, 0xfffffc0
	v_readlane_b32 s17, v253, 49
	v_readlane_b32 s18, v253, 50
	v_readlane_b32 s19, v253, 51
	v_readlane_b32 s20, v253, 52
	v_readlane_b32 s21, v253, 53
	v_readlane_b32 s22, v253, 54
	v_readlane_b32 s23, v253, 55
	v_readlane_b32 s24, v253, 56
	v_readlane_b32 s25, v253, 57
	v_readlane_b32 s26, v253, 58
	v_readlane_b32 s27, v253, 59
	v_readlane_b32 s30, v253, 62
	v_readlane_b32 s31, v253, 63
	s_cbranch_vccnz .LBB0_22
	v_ashrrev_i32_e32 v1, 7, v0
	v_bfe_u32 v2, v0, 5, 1
	v_lshlrev_b32_e32 v3, 8, v1
	v_lshlrev_b32_e32 v4, 4, v2
	v_lshlrev_b32_e32 v1, 6, v1
	v_lshl_or_b32 v156, v2, 2, v1
	v_and_b32_e32 v157, 0x5f, v0
	v_add_u32_e32 v158, v3, v4
	s_mov_b32 s8, s88
	s_branch .LBB0_12
